# P7 bf16 x1 stores widened (v_permlane16_swap between fq lane pairs) to one 16-byte write-through store per quad pair, so every large P7 store is sc1; otherwise v84
# speedup vs baseline: 1.0256x; 1.0172x over previous
.LBB0_508:
	v_lshl_add_u32 v142, s10, 8, v144
	v_lshl_or_b32 v140, s62, 8, v146
	v_lshl_add_u32 v150, v142, 10, v140
	v_lshlrev_b32_e32 v154, 2, v150
	v_lshlrev_b32_e32 v165, 1, v150
	v_bfe_u32 v140, v254, 4, 1
	v_mul_u32_u24_e32 v140, 24, v140
	v_add_u32_e32 v165, v165, v140
	v_add_u32_e32 v155, 0x10000, v154
	v_add_u32_e32 v166, 0x8000, v165
	v_add_u32_e32 v156, 0x20000, v154
	v_add_u32_e32 v167, 0x10000, v165
	v_add_u32_e32 v157, 0x30000, v154
	v_add_u32_e32 v168, 0x18000, v165
	v_add_u32_e32 v158, 0x80000, v154
	v_add_u32_e32 v169, 0x40000, v165
	v_add_u32_e32 v159, 0x90000, v154
	v_add_u32_e32 v170, 0x48000, v165
	v_add_u32_e32 v160, 0xa0000, v154
	v_add_u32_e32 v171, 0x50000, v165
	v_add_u32_e32 v161, 0xb0000, v154
	v_add_u32_e32 v172, 0x58000, v165
	v_cmp_lt_i32_e32 vcc, v162, v163
	s_nop 1
	v_cndmask_b32_e32 v173, v181, v162, vcc
	v_lshlrev_b32_e32 v173, 2, v173
	v_cmp_lt_i32_e32 vcc, v164, v163
	s_nop 1
	v_cndmask_b32_e32 v174, v181, v164, vcc
	v_lshlrev_b32_e32 v174, 2, v174
	s_lshl_b32 s48, s62, 4
	s_lshl_b32 s49, s55, 2
	s_add_i32 s48, s48, s49
	v_lshl_add_u32 v180, v142, 6, s48
	v_add_u32_e32 v175, 0x2000, v180
	global_load_dwordx4 v[182:185], v154, s[36:37]
	global_load_dwordx4 v[186:189], v154, s[36:37] offset:64
	global_load_dwordx4 v[190:193], v154, s[36:37] offset:512
	global_load_dwordx4 v[194:197], v154, s[36:37] offset:576
	global_load_dwordx4 v[198:201], v155, s[36:37]
	global_load_dwordx4 v[202:205], v155, s[36:37] offset:64
	global_load_dwordx4 v[206:209], v155, s[36:37] offset:512
	global_load_dwordx4 v[210:213], v155, s[36:37] offset:576
	global_load_dwordx4 v[214:217], v156, s[36:37]
	global_load_dwordx4 v[218:221], v156, s[36:37] offset:64
	global_load_dwordx4 v[222:225], v156, s[36:37] offset:512
	global_load_dwordx4 v[226:229], v156, s[36:37] offset:576
	global_load_dwordx4 v[230:233], v157, s[36:37]
	global_load_dwordx4 v[234:237], v157, s[36:37] offset:64
	global_load_dwordx4 v[238:241], v157, s[36:37] offset:512
	global_load_dwordx4 v[242:245], v157, s[36:37] offset:576
	s_waitcnt vmcnt(15)
	v_add_f32_e32 v124, v124, v182
	v_add_f32_e32 v125, v125, v183
	v_add_f32_e32 v126, v126, v184
	v_add_f32_e32 v127, v127, v185
	global_store_dwordx4 v154, v[124:127], s[30:31] sc1
	v_cvt_pk_bf16_f32 v176, v124, v125
	v_cvt_pk_bf16_f32 v177, v126, v127
	v_mul_f32_e32 v150, v125, v125
	v_mul_f32_e32 v140, v127, v127
	v_fmac_f32_e32 v150, v124, v124
	v_fmac_f32_e32 v140, v126, v126
	v_add_f32_e32 v246, v150, v140
	global_load_dwordx4 v[182:185], v158, s[36:37]
	s_waitcnt vmcnt(16)
	v_add_f32_e32 v120, v120, v186
	v_add_f32_e32 v121, v121, v187
	v_add_f32_e32 v122, v122, v188
	v_add_f32_e32 v123, v123, v189
	global_store_dwordx4 v154, v[120:123], s[30:31] offset:64 sc1
	v_cvt_pk_bf16_f32 v178, v120, v121
	v_cvt_pk_bf16_f32 v179, v122, v123
	v_mul_f32_e32 v150, v121, v121
	v_mul_f32_e32 v140, v123, v123
	v_permlane16_swap_b32 v176, v178
	v_permlane16_swap_b32 v177, v179
	global_store_dwordx4 v165, v[176:179], s[38:39] sc1
	v_fmac_f32_e32 v150, v120, v120
	v_fmac_f32_e32 v140, v122, v122
	v_add_f32_e32 v150, v150, v140
	v_add_f32_e32 v246, v246, v150
	global_load_dwordx4 v[186:189], v158, s[36:37] offset:64
	s_waitcnt vmcnt(18)
	v_add_f32_e32 v116, v116, v190
	v_add_f32_e32 v117, v117, v191
	v_add_f32_e32 v118, v118, v192
	v_add_f32_e32 v119, v119, v193
	global_store_dwordx4 v154, v[116:119], s[30:31] offset:512 sc1
	v_cvt_pk_bf16_f32 v176, v116, v117
	v_cvt_pk_bf16_f32 v177, v118, v119
	v_mul_f32_e32 v150, v117, v117
	v_mul_f32_e32 v140, v119, v119
	v_fmac_f32_e32 v150, v116, v116
	v_fmac_f32_e32 v140, v118, v118
	v_add_f32_e32 v150, v150, v140
	v_add_f32_e32 v246, v246, v150
	global_load_dwordx4 v[190:193], v158, s[36:37] offset:512
	s_waitcnt vmcnt(19)
	v_add_f32_e32 v112, v112, v194
	v_add_f32_e32 v113, v113, v195
	v_add_f32_e32 v114, v114, v196
	v_add_f32_e32 v115, v115, v197
	global_store_dwordx4 v154, v[112:115], s[30:31] offset:576 sc1
	v_cvt_pk_bf16_f32 v178, v112, v113
	v_cvt_pk_bf16_f32 v179, v114, v115
	v_mul_f32_e32 v150, v113, v113
	v_mul_f32_e32 v140, v115, v115
	v_permlane16_swap_b32 v176, v178
	v_permlane16_swap_b32 v177, v179
	global_store_dwordx4 v165, v[176:179], s[38:39] offset:256 sc1
	v_fmac_f32_e32 v150, v112, v112
	v_fmac_f32_e32 v140, v114, v114
	v_add_f32_e32 v150, v150, v140
	v_add_f32_e32 v246, v246, v150
	global_load_dwordx4 v[194:197], v158, s[36:37] offset:576
	s_waitcnt vmcnt(21)
	v_add_f32_e32 v108, v108, v198
	v_add_f32_e32 v109, v109, v199
	v_add_f32_e32 v110, v110, v200
	v_add_f32_e32 v111, v111, v201
	global_store_dwordx4 v155, v[108:111], s[30:31] sc1
	v_cvt_pk_bf16_f32 v176, v108, v109
	v_cvt_pk_bf16_f32 v177, v110, v111
	v_mul_f32_e32 v150, v109, v109
	v_mul_f32_e32 v140, v111, v111
	v_fmac_f32_e32 v150, v108, v108
	v_fmac_f32_e32 v140, v110, v110
	v_add_f32_e32 v247, v150, v140
	global_load_dwordx4 v[198:201], v159, s[36:37]
	s_waitcnt vmcnt(22)
	v_add_f32_e32 v104, v104, v202
	v_add_f32_e32 v105, v105, v203
	v_add_f32_e32 v106, v106, v204
	v_add_f32_e32 v107, v107, v205
	global_store_dwordx4 v155, v[104:107], s[30:31] offset:64 sc1
	v_cvt_pk_bf16_f32 v178, v104, v105
	v_cvt_pk_bf16_f32 v179, v106, v107
	v_mul_f32_e32 v150, v105, v105
	v_mul_f32_e32 v140, v107, v107
	v_permlane16_swap_b32 v176, v178
	v_permlane16_swap_b32 v177, v179
	global_store_dwordx4 v166, v[176:179], s[38:39] sc1
	v_fmac_f32_e32 v150, v104, v104
	v_fmac_f32_e32 v140, v106, v106
	v_add_f32_e32 v150, v150, v140
	v_add_f32_e32 v247, v247, v150
	global_load_dwordx4 v[202:205], v159, s[36:37] offset:64
	s_waitcnt vmcnt(24)
	v_add_f32_e32 v100, v100, v206
	v_add_f32_e32 v101, v101, v207
	v_add_f32_e32 v102, v102, v208
	v_add_f32_e32 v103, v103, v209
	global_store_dwordx4 v155, v[100:103], s[30:31] offset:512 sc1
	v_cvt_pk_bf16_f32 v176, v100, v101
	v_cvt_pk_bf16_f32 v177, v102, v103
	v_mul_f32_e32 v150, v101, v101
	v_mul_f32_e32 v140, v103, v103
	v_fmac_f32_e32 v150, v100, v100
	v_fmac_f32_e32 v140, v102, v102
	v_add_f32_e32 v150, v150, v140
	v_add_f32_e32 v247, v247, v150
	global_load_dwordx4 v[206:209], v159, s[36:37] offset:512
	s_waitcnt vmcnt(25)
	v_add_f32_e32 v96, v96, v210
	v_add_f32_e32 v97, v97, v211
	v_add_f32_e32 v98, v98, v212
	v_add_f32_e32 v99, v99, v213
	global_store_dwordx4 v155, v[96:99], s[30:31] offset:576 sc1
	v_cvt_pk_bf16_f32 v178, v96, v97
	v_cvt_pk_bf16_f32 v179, v98, v99
	v_mul_f32_e32 v150, v97, v97
	v_mul_f32_e32 v140, v99, v99
	v_permlane16_swap_b32 v176, v178
	v_permlane16_swap_b32 v177, v179
	global_store_dwordx4 v166, v[176:179], s[38:39] offset:256 sc1
	v_fmac_f32_e32 v150, v96, v96
	v_fmac_f32_e32 v140, v98, v98
	v_add_f32_e32 v150, v150, v140
	v_add_f32_e32 v247, v247, v150
	global_load_dwordx4 v[210:213], v159, s[36:37] offset:576
	s_waitcnt vmcnt(27)
	v_add_f32_e32 v92, v92, v214
	v_add_f32_e32 v93, v93, v215
	v_add_f32_e32 v94, v94, v216
	v_add_f32_e32 v95, v95, v217
	global_store_dwordx4 v156, v[92:95], s[30:31] sc1
	v_cvt_pk_bf16_f32 v176, v92, v93
	v_cvt_pk_bf16_f32 v177, v94, v95
	v_mul_f32_e32 v150, v93, v93
	v_mul_f32_e32 v140, v95, v95
	v_fmac_f32_e32 v150, v92, v92
	v_fmac_f32_e32 v140, v94, v94
	v_add_f32_e32 v248, v150, v140
	global_load_dwordx4 v[214:217], v160, s[36:37]
	s_waitcnt vmcnt(28)
	v_add_f32_e32 v88, v88, v218
	v_add_f32_e32 v89, v89, v219
	v_add_f32_e32 v90, v90, v220
	v_add_f32_e32 v91, v91, v221
	global_store_dwordx4 v156, v[88:91], s[30:31] offset:64 sc1
	v_cvt_pk_bf16_f32 v178, v88, v89
	v_cvt_pk_bf16_f32 v179, v90, v91
	v_mul_f32_e32 v150, v89, v89
	v_mul_f32_e32 v140, v91, v91
	v_permlane16_swap_b32 v176, v178
	v_permlane16_swap_b32 v177, v179
	global_store_dwordx4 v167, v[176:179], s[38:39] sc1
	v_fmac_f32_e32 v150, v88, v88
	v_fmac_f32_e32 v140, v90, v90
	v_add_f32_e32 v150, v150, v140
	v_add_f32_e32 v248, v248, v150
	global_load_dwordx4 v[218:221], v160, s[36:37] offset:64
	s_waitcnt vmcnt(30)
	v_add_f32_e32 v84, v84, v222
	v_add_f32_e32 v85, v85, v223
	v_add_f32_e32 v86, v86, v224
	v_add_f32_e32 v87, v87, v225
	global_store_dwordx4 v156, v[84:87], s[30:31] offset:512 sc1
	v_cvt_pk_bf16_f32 v176, v84, v85
	v_cvt_pk_bf16_f32 v177, v86, v87
	v_mul_f32_e32 v150, v85, v85
	v_mul_f32_e32 v140, v87, v87
	v_fmac_f32_e32 v150, v84, v84
	v_fmac_f32_e32 v140, v86, v86
	v_add_f32_e32 v150, v150, v140
	v_add_f32_e32 v248, v248, v150
	global_load_dwordx4 v[222:225], v160, s[36:37] offset:512
	s_waitcnt vmcnt(31)
	v_add_f32_e32 v80, v80, v226
	v_add_f32_e32 v81, v81, v227
	v_add_f32_e32 v82, v82, v228
	v_add_f32_e32 v83, v83, v229
	global_store_dwordx4 v156, v[80:83], s[30:31] offset:576 sc1
	v_cvt_pk_bf16_f32 v178, v80, v81
	v_cvt_pk_bf16_f32 v179, v82, v83
	v_mul_f32_e32 v150, v81, v81
	v_mul_f32_e32 v140, v83, v83
	v_permlane16_swap_b32 v176, v178
	v_permlane16_swap_b32 v177, v179
	global_store_dwordx4 v167, v[176:179], s[38:39] offset:256 sc1
	v_fmac_f32_e32 v150, v80, v80
	v_fmac_f32_e32 v140, v82, v82
	v_add_f32_e32 v150, v150, v140
	v_add_f32_e32 v248, v248, v150
	global_load_dwordx4 v[226:229], v160, s[36:37] offset:576
	s_waitcnt vmcnt(33)
	v_add_f32_e32 v76, v76, v230
	v_add_f32_e32 v77, v77, v231
	v_add_f32_e32 v78, v78, v232
	v_add_f32_e32 v79, v79, v233
	global_store_dwordx4 v157, v[76:79], s[30:31] sc1
	v_cvt_pk_bf16_f32 v176, v76, v77
	v_cvt_pk_bf16_f32 v177, v78, v79
	v_mul_f32_e32 v150, v77, v77
	v_mul_f32_e32 v140, v79, v79
	v_fmac_f32_e32 v150, v76, v76
	v_fmac_f32_e32 v140, v78, v78
	v_add_f32_e32 v249, v150, v140
	global_load_dwordx4 v[230:233], v161, s[36:37]
	s_waitcnt vmcnt(34)
	v_add_f32_e32 v72, v72, v234
	v_add_f32_e32 v73, v73, v235
	v_add_f32_e32 v74, v74, v236
	v_add_f32_e32 v75, v75, v237
	global_store_dwordx4 v157, v[72:75], s[30:31] offset:64 sc1
	v_cvt_pk_bf16_f32 v178, v72, v73
	v_cvt_pk_bf16_f32 v179, v74, v75
	v_mul_f32_e32 v150, v73, v73
	v_mul_f32_e32 v140, v75, v75
	v_permlane16_swap_b32 v176, v178
	v_permlane16_swap_b32 v177, v179
	global_store_dwordx4 v168, v[176:179], s[38:39] sc1
	v_fmac_f32_e32 v150, v72, v72
	v_fmac_f32_e32 v140, v74, v74
	v_add_f32_e32 v150, v150, v140
	v_add_f32_e32 v249, v249, v150
	global_load_dwordx4 v[234:237], v161, s[36:37] offset:64
	s_waitcnt vmcnt(36)
	v_add_f32_e32 v68, v68, v238
	v_add_f32_e32 v69, v69, v239
	v_add_f32_e32 v70, v70, v240
	v_add_f32_e32 v71, v71, v241
	global_store_dwordx4 v157, v[68:71], s[30:31] offset:512 sc1
	v_cvt_pk_bf16_f32 v176, v68, v69
	v_cvt_pk_bf16_f32 v177, v70, v71
	v_mul_f32_e32 v150, v69, v69
	v_mul_f32_e32 v140, v71, v71
	v_fmac_f32_e32 v150, v68, v68
	v_fmac_f32_e32 v140, v70, v70
	v_add_f32_e32 v150, v150, v140
	v_add_f32_e32 v249, v249, v150
	global_load_dwordx4 v[238:241], v161, s[36:37] offset:512
	s_waitcnt vmcnt(37)
	v_add_f32_e32 v64, v64, v242
	v_add_f32_e32 v65, v65, v243
	v_add_f32_e32 v66, v66, v244
	v_add_f32_e32 v67, v67, v245
	global_store_dwordx4 v157, v[64:67], s[30:31] offset:576 sc1
	v_cvt_pk_bf16_f32 v178, v64, v65
	v_cvt_pk_bf16_f32 v179, v66, v67
	v_mul_f32_e32 v150, v65, v65
	v_mul_f32_e32 v140, v67, v67
	v_permlane16_swap_b32 v176, v178
	v_permlane16_swap_b32 v177, v179
	global_store_dwordx4 v168, v[176:179], s[38:39] offset:256 sc1
	v_fmac_f32_e32 v150, v64, v64
	v_fmac_f32_e32 v140, v66, v66
	v_add_f32_e32 v150, v150, v140
	v_add_f32_e32 v249, v249, v150
	global_load_dwordx4 v[242:245], v161, s[36:37] offset:576
	s_waitcnt vmcnt(38)
	v_add_f32_e32 v60, v60, v182
	v_add_f32_e32 v61, v61, v183
	v_add_f32_e32 v62, v62, v184
	v_add_f32_e32 v63, v63, v185
	global_store_dwordx4 v158, v[60:63], s[30:31] sc1
	v_cvt_pk_bf16_f32 v176, v60, v61
	v_cvt_pk_bf16_f32 v177, v62, v63
	v_mul_f32_e32 v150, v61, v61
	v_mul_f32_e32 v140, v63, v63
	v_fmac_f32_e32 v150, v60, v60
	v_fmac_f32_e32 v140, v62, v62
	v_add_f32_e32 v250, v150, v140
	s_waitcnt vmcnt(36)
	v_add_f32_e32 v56, v56, v186
	v_add_f32_e32 v57, v57, v187
	v_add_f32_e32 v58, v58, v188
	v_add_f32_e32 v59, v59, v189
	global_store_dwordx4 v158, v[56:59], s[30:31] offset:64 sc1
	v_cvt_pk_bf16_f32 v178, v56, v57
	v_cvt_pk_bf16_f32 v179, v58, v59
	v_mul_f32_e32 v150, v57, v57
	v_mul_f32_e32 v140, v59, v59
	v_permlane16_swap_b32 v176, v178
	v_permlane16_swap_b32 v177, v179
	global_store_dwordx4 v169, v[176:179], s[38:39] sc1
	v_fmac_f32_e32 v150, v56, v56
	v_fmac_f32_e32 v140, v58, v58
	v_add_f32_e32 v150, v150, v140
	v_add_f32_e32 v250, v250, v150
	s_waitcnt vmcnt(36)
	v_add_f32_e32 v52, v52, v190
	v_add_f32_e32 v53, v53, v191
	v_add_f32_e32 v54, v54, v192
	v_add_f32_e32 v55, v55, v193
	global_store_dwordx4 v158, v[52:55], s[30:31] offset:512 sc1
	v_cvt_pk_bf16_f32 v176, v52, v53
	v_cvt_pk_bf16_f32 v177, v54, v55
	v_mul_f32_e32 v150, v53, v53
	v_mul_f32_e32 v140, v55, v55
	v_fmac_f32_e32 v150, v52, v52
	v_fmac_f32_e32 v140, v54, v54
	v_add_f32_e32 v150, v150, v140
	v_add_f32_e32 v250, v250, v150
	s_waitcnt vmcnt(34)
	v_add_f32_e32 v48, v48, v194
	v_add_f32_e32 v49, v49, v195
	v_add_f32_e32 v50, v50, v196
	v_add_f32_e32 v51, v51, v197
	global_store_dwordx4 v158, v[48:51], s[30:31] offset:576 sc1
	v_cvt_pk_bf16_f32 v178, v48, v49
	v_cvt_pk_bf16_f32 v179, v50, v51
	v_mul_f32_e32 v150, v49, v49
	v_mul_f32_e32 v140, v51, v51
	v_permlane16_swap_b32 v176, v178
	v_permlane16_swap_b32 v177, v179
	global_store_dwordx4 v169, v[176:179], s[38:39] offset:256 sc1
	v_fmac_f32_e32 v150, v48, v48
	v_fmac_f32_e32 v140, v50, v50
	v_add_f32_e32 v150, v150, v140
	v_add_f32_e32 v250, v250, v150
	s_waitcnt vmcnt(34)
	v_add_f32_e32 v44, v44, v198
	v_add_f32_e32 v45, v45, v199
	v_add_f32_e32 v46, v46, v200
	v_add_f32_e32 v47, v47, v201
	global_store_dwordx4 v159, v[44:47], s[30:31] sc1
	v_cvt_pk_bf16_f32 v176, v44, v45
	v_cvt_pk_bf16_f32 v177, v46, v47
	v_mul_f32_e32 v150, v45, v45
	v_mul_f32_e32 v140, v47, v47
	v_fmac_f32_e32 v150, v44, v44
	v_fmac_f32_e32 v140, v46, v46
	v_add_f32_e32 v251, v150, v140
	s_waitcnt vmcnt(32)
	v_add_f32_e32 v40, v40, v202
	v_add_f32_e32 v41, v41, v203
	v_add_f32_e32 v42, v42, v204
	v_add_f32_e32 v43, v43, v205
	global_store_dwordx4 v159, v[40:43], s[30:31] offset:64 sc1
	v_cvt_pk_bf16_f32 v178, v40, v41
	v_cvt_pk_bf16_f32 v179, v42, v43
	v_mul_f32_e32 v150, v41, v41
	v_mul_f32_e32 v140, v43, v43
	v_permlane16_swap_b32 v176, v178
	v_permlane16_swap_b32 v177, v179
	global_store_dwordx4 v170, v[176:179], s[38:39] sc1
	v_fmac_f32_e32 v150, v40, v40
	v_fmac_f32_e32 v140, v42, v42
	v_add_f32_e32 v150, v150, v140
	v_add_f32_e32 v251, v251, v150
	s_waitcnt vmcnt(32)
	v_add_f32_e32 v36, v36, v206
	v_add_f32_e32 v37, v37, v207
	v_add_f32_e32 v38, v38, v208
	v_add_f32_e32 v39, v39, v209
	global_store_dwordx4 v159, v[36:39], s[30:31] offset:512 sc1
	v_cvt_pk_bf16_f32 v176, v36, v37
	v_cvt_pk_bf16_f32 v177, v38, v39
	v_mul_f32_e32 v150, v37, v37
	v_mul_f32_e32 v140, v39, v39
	v_fmac_f32_e32 v150, v36, v36
	v_fmac_f32_e32 v140, v38, v38
	v_add_f32_e32 v150, v150, v140
	v_add_f32_e32 v251, v251, v150
	s_waitcnt vmcnt(30)
	v_add_f32_e32 v32, v32, v210
	v_add_f32_e32 v33, v33, v211
	v_add_f32_e32 v34, v34, v212
	v_add_f32_e32 v35, v35, v213
	global_store_dwordx4 v159, v[32:35], s[30:31] offset:576 sc1
	v_cvt_pk_bf16_f32 v178, v32, v33
	v_cvt_pk_bf16_f32 v179, v34, v35
	v_mul_f32_e32 v150, v33, v33
	v_mul_f32_e32 v140, v35, v35
	v_permlane16_swap_b32 v176, v178
	v_permlane16_swap_b32 v177, v179
	global_store_dwordx4 v170, v[176:179], s[38:39] offset:256 sc1
	v_fmac_f32_e32 v150, v32, v32
	v_fmac_f32_e32 v140, v34, v34
	v_add_f32_e32 v150, v150, v140
	v_add_f32_e32 v251, v251, v150
	s_waitcnt vmcnt(30)
	v_add_f32_e32 v28, v28, v214
	v_add_f32_e32 v29, v29, v215
	v_add_f32_e32 v30, v30, v216
	v_add_f32_e32 v31, v31, v217
	global_store_dwordx4 v160, v[28:31], s[30:31] sc1
	v_cvt_pk_bf16_f32 v176, v28, v29
	v_cvt_pk_bf16_f32 v177, v30, v31
	v_mul_f32_e32 v150, v29, v29
	v_mul_f32_e32 v140, v31, v31
	v_fmac_f32_e32 v150, v28, v28
	v_fmac_f32_e32 v140, v30, v30
	v_add_f32_e32 v252, v150, v140
	s_waitcnt vmcnt(28)
	v_add_f32_e32 v24, v24, v218
	v_add_f32_e32 v25, v25, v219
	v_add_f32_e32 v26, v26, v220
	v_add_f32_e32 v27, v27, v221
	global_store_dwordx4 v160, v[24:27], s[30:31] offset:64 sc1
	v_cvt_pk_bf16_f32 v178, v24, v25
	v_cvt_pk_bf16_f32 v179, v26, v27
	v_mul_f32_e32 v150, v25, v25
	v_mul_f32_e32 v140, v27, v27
	v_permlane16_swap_b32 v176, v178
	v_permlane16_swap_b32 v177, v179
	global_store_dwordx4 v171, v[176:179], s[38:39] sc1
	v_fmac_f32_e32 v150, v24, v24
	v_fmac_f32_e32 v140, v26, v26
	v_add_f32_e32 v150, v150, v140
	v_add_f32_e32 v252, v252, v150
	s_waitcnt vmcnt(28)
	v_add_f32_e32 v20, v20, v222
	v_add_f32_e32 v21, v21, v223
	v_add_f32_e32 v22, v22, v224
	v_add_f32_e32 v23, v23, v225
	global_store_dwordx4 v160, v[20:23], s[30:31] offset:512 sc1
	v_cvt_pk_bf16_f32 v176, v20, v21
	v_cvt_pk_bf16_f32 v177, v22, v23
	v_mul_f32_e32 v150, v21, v21
	v_mul_f32_e32 v140, v23, v23
	v_fmac_f32_e32 v150, v20, v20
	v_fmac_f32_e32 v140, v22, v22
	v_add_f32_e32 v150, v150, v140
	v_add_f32_e32 v252, v252, v150
	s_waitcnt vmcnt(26)
	v_add_f32_e32 v16, v16, v226
	v_add_f32_e32 v17, v17, v227
	v_add_f32_e32 v18, v18, v228
	v_add_f32_e32 v19, v19, v229
	global_store_dwordx4 v160, v[16:19], s[30:31] offset:576 sc1
	v_cvt_pk_bf16_f32 v178, v16, v17
	v_cvt_pk_bf16_f32 v179, v18, v19
	v_mul_f32_e32 v150, v17, v17
	v_mul_f32_e32 v140, v19, v19
	v_permlane16_swap_b32 v176, v178
	v_permlane16_swap_b32 v177, v179
	global_store_dwordx4 v171, v[176:179], s[38:39] offset:256 sc1
	v_fmac_f32_e32 v150, v16, v16
	v_fmac_f32_e32 v140, v18, v18
	v_add_f32_e32 v150, v150, v140
	v_add_f32_e32 v252, v252, v150
	s_waitcnt vmcnt(26)
	v_add_f32_e32 v12, v12, v230
	v_add_f32_e32 v13, v13, v231
	v_add_f32_e32 v14, v14, v232
	v_add_f32_e32 v15, v15, v233
	global_store_dwordx4 v161, v[12:15], s[30:31] sc1
	v_cvt_pk_bf16_f32 v176, v12, v13
	v_cvt_pk_bf16_f32 v177, v14, v15
	v_mul_f32_e32 v150, v13, v13
	v_mul_f32_e32 v140, v15, v15
	v_fmac_f32_e32 v150, v12, v12
	v_fmac_f32_e32 v140, v14, v14
	v_add_f32_e32 v253, v150, v140
	s_waitcnt vmcnt(24)
	v_add_f32_e32 v8, v8, v234
	v_add_f32_e32 v9, v9, v235
	v_add_f32_e32 v10, v10, v236
	v_add_f32_e32 v11, v11, v237
	global_store_dwordx4 v161, v[8:11], s[30:31] offset:64 sc1
	v_cvt_pk_bf16_f32 v178, v8, v9
	v_cvt_pk_bf16_f32 v179, v10, v11
	v_mul_f32_e32 v150, v9, v9
	v_mul_f32_e32 v140, v11, v11
	v_permlane16_swap_b32 v176, v178
	v_permlane16_swap_b32 v177, v179
	global_store_dwordx4 v172, v[176:179], s[38:39] sc1
	v_fmac_f32_e32 v150, v8, v8
	v_fmac_f32_e32 v140, v10, v10
	v_add_f32_e32 v150, v150, v140
	v_add_f32_e32 v253, v253, v150
	s_waitcnt vmcnt(24)
	v_add_f32_e32 v4, v4, v238
	v_add_f32_e32 v5, v5, v239
	v_add_f32_e32 v6, v6, v240
	v_add_f32_e32 v7, v7, v241
	global_store_dwordx4 v161, v[4:7], s[30:31] offset:512 sc1
	v_cvt_pk_bf16_f32 v176, v4, v5
	v_cvt_pk_bf16_f32 v177, v6, v7
	v_mul_f32_e32 v150, v5, v5
	v_mul_f32_e32 v140, v7, v7
	v_fmac_f32_e32 v150, v4, v4
	v_fmac_f32_e32 v140, v6, v6
	v_add_f32_e32 v150, v150, v140
	v_add_f32_e32 v253, v253, v150
	s_waitcnt vmcnt(22)
	v_add_f32_e32 v0, v0, v242
	v_add_f32_e32 v1, v1, v243
	v_add_f32_e32 v2, v2, v244
	v_add_f32_e32 v3, v3, v245
	global_store_dwordx4 v161, v[0:3], s[30:31] offset:576 sc1
	v_cvt_pk_bf16_f32 v178, v0, v1
	v_cvt_pk_bf16_f32 v179, v2, v3
	v_mul_f32_e32 v150, v1, v1
	v_mul_f32_e32 v140, v3, v3
	v_permlane16_swap_b32 v176, v178
	v_permlane16_swap_b32 v177, v179
	global_store_dwordx4 v172, v[176:179], s[38:39] offset:256 sc1
	v_fmac_f32_e32 v150, v0, v0
	v_fmac_f32_e32 v140, v2, v2
	v_add_f32_e32 v150, v150, v140
	v_add_f32_e32 v253, v253, v150
	ds_bpermute_b32 v182, v173, v246
	ds_bpermute_b32 v183, v173, v247
	ds_bpermute_b32 v184, v173, v248
	ds_bpermute_b32 v185, v173, v249
	ds_bpermute_b32 v186, v173, v250
	ds_bpermute_b32 v187, v173, v251
	ds_bpermute_b32 v188, v173, v252
	ds_bpermute_b32 v189, v173, v253
	s_waitcnt lgkmcnt(0)
	v_add_f32_e32 v246, v246, v182
	v_add_f32_e32 v247, v247, v183
	v_add_f32_e32 v248, v248, v184
	v_add_f32_e32 v249, v249, v185
	v_add_f32_e32 v250, v250, v186
	v_add_f32_e32 v251, v251, v187
	v_add_f32_e32 v252, v252, v188
	v_add_f32_e32 v253, v253, v189
	ds_bpermute_b32 v182, v174, v246
	ds_bpermute_b32 v183, v174, v247
	ds_bpermute_b32 v184, v174, v248
	ds_bpermute_b32 v185, v174, v249
	ds_bpermute_b32 v186, v174, v250
	ds_bpermute_b32 v187, v174, v251
	ds_bpermute_b32 v188, v174, v252
	ds_bpermute_b32 v189, v174, v253
	s_waitcnt lgkmcnt(0)
	v_add_f32_e32 v246, v246, v182
	v_add_f32_e32 v247, v247, v183
	v_add_f32_e32 v248, v248, v184
	v_add_f32_e32 v249, v249, v185
	v_add_f32_e32 v250, v250, v186
	v_add_f32_e32 v251, v251, v187
	v_add_f32_e32 v252, v252, v188
	v_add_f32_e32 v253, v253, v189
	s_and_saveexec_b64 s[50:51], s[6:7]
	global_store_dword v180, v246, s[40:41]
	global_store_dword v180, v247, s[40:41] offset:1024
	global_store_dword v180, v248, s[40:41] offset:2048
	global_store_dword v180, v249, s[40:41] offset:3072
	global_store_dword v175, v250, s[40:41]
	global_store_dword v175, v251, s[40:41] offset:1024
	global_store_dword v175, v252, s[40:41] offset:2048
	global_store_dword v175, v253, s[40:41] offset:3072
